# MLA attention: K-part (k_nope,k_rope) staging ds_writes moved ahead of the first per-tile barrier (their LDS buffers are already free), only V writes stay between the barriers
# baseline (speedup 1.0000x reference)
; __device__ __forceinline__ void finishSM(f32x16& p0, f32x16& p1, float alpha, float& l_reg, bf16x8& pa0, bf16x8& pa1, bf16x8& pa2, bf16x8& pa3) {
; #pragma unroll
;   for (int r = 0; r < 16; ++r) p1[r] = __builtin_amdgcn_exp2f(p1[r]);
;   float ps = 0;
; #pragma unroll
;   for (int r = 0; r < 16; ++r) ps += p0[r];
; #pragma unroll
;   for (int r = 0; r < 16; ++r) ps += p1[r];
;   { auto rr = __builtin_amdgcn_permlane32_swap(__float_as_uint(ps), __float_as_uint(ps), false, false);
;     ps = __uint_as_float(rr[0]) + __uint_as_float(rr[1]); }
;   l_reg = l_reg * alpha + ps;
; __device__ __forceinline__ void qkt_mla(f32x16& p0, f32x16& p1, const char* Kn, const char* Kr, const char* Qr, const bf16x8* qr, const f32x16& negm, int r32, int hi) {
; #pragma unroll
;   for (int d0 = 0; d0 < 8; ++d0) { const int cb = (d0 * 16 + hi * 8) * 2;
;     const bf16x8 b0 = *reinterpret_cast<const bf16x8*>(Kn + KSWZ(r32, cb));
;     const bf16x8 b1 = *reinterpret_cast<const bf16x8*>(Kn + KSWZ(32 + r32, cb));
;     bf16x8 q; if (d0 < 4) q = qr[d0]; else q = *reinterpret_cast<const bf16x8*>(Qr + KSWZ(r32, ((d0 - 4) * 16 + hi * 8) * 2));
;     if (d0 == 0) { p0 = __builtin_amdgcn_mfma_f32_32x32x16_bf16(b0, q, negm, 0, 0, 0); p1 = __builtin_amdgcn_mfma_f32_32x32x16_bf16(b1, q, negm, 0, 0, 0); }
;     else { p0 = __builtin_amdgcn_mfma_f32_32x32x16_bf16(b0, q, p0, 0, 0, 0); p1 = __builtin_amdgcn_mfma_f32_32x32x16_bf16(b1, q, p1, 0, 0, 0); } }
; #pragma unroll
;   for (int d0 = 0; d0 < 4; ++d0) { const int cb = (d0 * 16 + hi * 8) * 2;
;     const bf16x8 b0 = *reinterpret_cast<const bf16x8*>(Kr + KSWZ2(r32, cb));
;     const bf16x8 b1 = *reinterpret_cast<const bf16x8*>(Kr + KSWZ2(32 + r32, cb));
;     const bf16x8 q = *reinterpret_cast<const bf16x8*>(Qr + KSWZ(r32, ((4 + d0) * 16 + hi * 8) * 2));
;     p0 = __builtin_amdgcn_mfma_f32_32x32x16_bf16(b0, q, p0, 0, 0, 0);
;     p1 = __builtin_amdgcn_mfma_f32_32x32x16_bf16(b1, q, p1, 0, 0, 0); }
.LBB0_723:
	ds_read_b128 v[98:101], v181 offset:49152
	ds_read_b128 v[218:221], v181 offset:57344
	s_add_i32 s8, 0, 0x12000
	v_add_f32_e32 v150, 0, v151
	v_add_f32_e32 v150, v152, v150
	s_waitcnt lgkmcnt(1)
	v_mfma_f32_32x32x16_bf16 v[114:129], v[98:101], v[142:145], v[66:81]
	v_add_f32_e32 v150, v175, v150
	v_add_f32_e32 v150, v226, v150
	v_add_u32_e32 v217, s8, v208
	v_add_f32_e32 v150, v227, v150
	v_add_f32_e32 v150, v228, v150
	v_add_f32_e32 v150, v153, v150
	v_add_f32_e32 v150, v174, v150
	s_waitcnt lgkmcnt(0)
	v_mfma_f32_32x32x16_bf16 v[98:113], v[218:221], v[142:145], v[66:81]
	ds_read_b128 v[218:221], v192 offset:49152
	ds_read_b128 v[222:225], v192 offset:57344
	v_add_f32_e32 v150, v149, v150
	v_add_f32_e32 v150, v171, v150
	v_add_f32_e32 v150, v172, v150
	v_add_f32_e32 v150, v173, v150
	v_exp_f32_e32 v82, v82
	v_add_f32_e32 v150, v146, v150
	s_waitcnt lgkmcnt(1)
	v_mfma_f32_32x32x16_bf16 v[114:129], v[218:221], v[138:141], v[114:129]
	v_exp_f32_e32 v83, v83
	v_add_f32_e32 v150, v147, v150
	v_exp_f32_e32 v84, v84
	v_add_f32_e32 v150, v148, v150
	v_exp_f32_e32 v85, v85
	v_add_f32_e32 v150, v170, v150
	v_exp_f32_e32 v86, v86
	s_waitcnt lgkmcnt(0)
	v_mfma_f32_32x32x16_bf16 v[98:113], v[222:225], v[138:141], v[98:113]
	ds_read_b128 v[218:221], v193 offset:49152
	ds_read_b128 v[222:225], v193 offset:57344
	v_add_f32_e32 v150, v82, v150
	v_exp_f32_e32 v87, v87
	v_add_f32_e32 v150, v83, v150
	v_exp_f32_e32 v88, v88
	v_add_f32_e32 v150, v84, v150
	v_exp_f32_e32 v89, v89
	s_waitcnt lgkmcnt(1)
	v_mfma_f32_32x32x16_bf16 v[114:129], v[218:221], v[134:137], v[114:129]
	v_add_f32_e32 v150, v85, v150
	v_exp_f32_e32 v90, v90
	v_add_f32_e32 v150, v86, v150
	v_exp_f32_e32 v91, v91
	v_add_f32_e32 v150, v87, v150
	v_exp_f32_e32 v92, v92
	v_add_f32_e32 v150, v88, v150
	s_waitcnt lgkmcnt(0)
	v_mfma_f32_32x32x16_bf16 v[98:113], v[222:225], v[134:137], v[98:113]
	ds_read_b128 v[218:221], v195 offset:49152
	ds_read_b128 v[222:225], v195 offset:57344
	v_exp_f32_e32 v93, v93
	v_add_f32_e32 v150, v89, v150
	v_exp_f32_e32 v94, v94
	v_add_f32_e32 v150, v90, v150
	v_exp_f32_e32 v95, v95
	v_add_f32_e32 v150, v91, v150
	s_waitcnt lgkmcnt(1)
	v_mfma_f32_32x32x16_bf16 v[114:129], v[218:221], v[130:133], v[114:129]
	v_exp_f32_e32 v96, v96
	v_add_f32_e32 v150, v92, v150
	v_exp_f32_e32 v97, v97
	v_add_f32_e32 v150, v93, v150
	v_add_f32_e32 v150, v94, v150
	v_add_f32_e32 v150, v95, v150
	v_add_f32_e32 v150, v96, v150
	s_waitcnt lgkmcnt(0)
	v_mfma_f32_32x32x16_bf16 v[98:113], v[222:225], v[130:133], v[98:113]
	ds_read_b128 v[218:221], v197 offset:49152
	ds_read_b128 v[222:225], v197 offset:57344
	ds_read_b128 v[230:233], v199
	v_cvt_pk_bf16_f32 v153, v153, v174
	v_cvt_pk_bf16_f32 v229, v84, v85
	s_waitcnt lgkmcnt(0)
	v_mfma_f32_32x32x16_bf16 v[114:129], v[218:221], v[230:233], v[114:129]
	v_mfma_f32_32x32x16_bf16 v[98:113], v[222:225], v[230:233], v[98:113]
	ds_read_b128 v[218:221], v191 offset:49152
	ds_read_b128 v[222:225], v191 offset:57344
	ds_read_b128 v[230:233], v201
	s_waitcnt lgkmcnt(0)
	v_mfma_f32_32x32x16_bf16 v[114:129], v[218:221], v[230:233], v[114:129]
	v_mfma_f32_32x32x16_bf16 v[98:113], v[222:225], v[230:233], v[98:113]
	ds_read_b128 v[218:221], v196 offset:49152
	ds_read_b128 v[222:225], v196 offset:57344
	ds_read_b128 v[230:233], v200
	s_waitcnt lgkmcnt(0)
	v_mfma_f32_32x32x16_bf16 v[114:129], v[218:221], v[230:233], v[114:129]
	v_mfma_f32_32x32x16_bf16 v[98:113], v[222:225], v[230:233], v[98:113]
	ds_read_b128 v[218:221], v194 offset:49152
	ds_read_b128 v[222:225], v194 offset:57344
	ds_read_b128 v[230:233], v204
	s_waitcnt lgkmcnt(0)
	v_mfma_f32_32x32x16_bf16 v[114:129], v[218:221], v[230:233], v[114:129]
	v_add_u32_e32 v218, s8, v206
	v_add_u32_e32 v219, s8, v210
	v_mfma_f32_32x32x16_bf16 v[98:113], v[222:225], v[230:233], v[98:113]
	ds_read_b128 v[220:223], v218
	ds_read_b128 v[230:233], v218 offset:4096
	ds_read_b128 v[234:237], v205
	s_waitcnt lgkmcnt(0)
	v_mfma_f32_32x32x16_bf16 v[114:129], v[220:223], v[234:237], v[114:129]
	v_mfma_f32_32x32x16_bf16 v[98:113], v[230:233], v[234:237], v[98:113]
	ds_read_b128 v[220:223], v217
	ds_read_b128 v[230:233], v217 offset:4096
	ds_read_b128 v[234:237], v203
	s_waitcnt lgkmcnt(0)
	v_mfma_f32_32x32x16_bf16 v[114:129], v[220:223], v[234:237], v[114:129]
	v_mfma_f32_32x32x16_bf16 v[98:113], v[230:233], v[234:237], v[98:113]
	ds_read_b128 v[220:223], v219
	ds_read_b128 v[230:233], v219 offset:4096
	ds_read_b128 v[234:237], v202
	s_waitcnt lgkmcnt(0)
	v_mfma_f32_32x32x16_bf16 v[114:129], v[220:223], v[234:237], v[114:129]
	v_add_u32_e32 v220, s8, v212
	v_add_f32_e32 v221, v97, v150
	v_cvt_pk_bf16_f32 v150, v151, v152
	v_cvt_pk_bf16_f32 v152, v227, v228
	v_cvt_pk_bf16_f32 v151, v175, v226
	s_nop 0
	v_permlane32_swap_b32_e32 v150, v152
	v_mfma_f32_32x32x16_bf16 v[98:113], v[230:233], v[234:237], v[98:113]
	ds_read_b128 v[222:225], v220
	ds_read_b128 v[230:233], v220 offset:4096
	ds_read_b128 v[234:237], v198
	v_cvt_pk_bf16_f32 v226, v146, v147
	v_cvt_pk_bf16_f32 v227, v148, v170
	v_cvt_pk_bf16_f32 v228, v82, v83
	v_permlane32_swap_b32_e32 v151, v153
	s_waitcnt lgkmcnt(0)
; #define SBAR() __builtin_amdgcn_sched_barrier(0)
; template <bool MLA> __device__ __forceinline__ void partialSM(f32x16& p0, f32x16& p1, float& m_reg, float& mn, float& alpha) {
;   constexpr float SCALE = MLA ? 0.07216878364870322f : 0.125f;
;   constexpr float C = SCALE * 1.4426950408889634f;
;   float pmax = p0[0];
; #pragma unroll
;   for (int r = 1; r < 16; ++r) pmax = fmaxf(pmax, p0[r]);
; #pragma unroll
;   for (int r = 0; r < 16; ++r) pmax = fmaxf(pmax, p1[r]);
;   { auto rr = __builtin_amdgcn_permlane32_swap(__float_as_uint(pmax), __float_as_uint(pmax), false, false);
;     pmax = fmaxf(__uint_as_float(rr[0]), __uint_as_float(rr[1])); }
;   if (__builtin_expect(__all(pmax - m_reg <= THR / SCALE), 1)) { mn = m_reg; alpha = 1.f; }
; template <int D0> __device__ __forceinline__ void pv_one(f32x16& od, int vb, bf16x8 pa0, bf16x8 pa1, bf16x8 pa2, bf16x8 pa3) {
;   const s16x4 l0 = tr_read<v_rd_off(D0, 0, 0)>(vb), h0 = tr_read<v_rd_off(D0, 0, 1)>(vb), l1 = tr_read<v_rd_off(D0, 1, 0)>(vb), h1 = tr_read<v_rd_off(D0, 1, 1)>(vb);
;   const s16x4 l2 = tr_read<v_rd_off(D0, 2, 0)>(vb), h2 = tr_read<v_rd_off(D0, 2, 1)>(vb), l3 = tr_read<v_rd_off(D0, 3, 0)>(vb), h3 = tr_read<v_rd_off(D0, 3, 1)>(vb);
;   asm volatile("s_waitcnt lgkmcnt(0)" ::: "memory"); SBAR();
;     ...
;   od = __builtin_amdgcn_mfma_f32_32x32x16_bf16(pa0, PK(l0, h0), od, 0, 0, 0);
;   od = __builtin_amdgcn_mfma_f32_32x32x16_bf16(pa1, PK(l1, h1), od, 0, 0, 0);
;   od = __builtin_amdgcn_mfma_f32_32x32x16_bf16(pa2, PK(l2, h2), od, 0, 0, 0);
;   od = __builtin_amdgcn_mfma_f32_32x32x16_bf16(pa3, PK(l3, h3), od, 0, 0, 0);
;     ...
; }
; __device__ __forceinline__ void pv_d0(f32x16* o, int vb, bf16x8 pa0, bf16x8 pa1, bf16x8 pa2, bf16x8 pa3) {
;   pv_one<0>(o[0], vb, pa0, pa1, pa2, pa3); pv_one<1>(o[1], vb, pa0, pa1, pa2, pa3); pv_one<2>(o[2], vb, pa0, pa1, pa2, pa3); pv_one<3>(o[3], vb, pa0, pa1, pa2, pa3);
	v_mfma_f32_32x32x16_bf16 v[114:129], v[222:225], v[234:237], v[114:129]
	v_mov_b32_e32 v222, v221
	s_nop 1
	v_permlane32_swap_b32_e32 v221, v222
	v_cvt_pk_bf16_f32 v224, v149, v171
	v_cvt_pk_bf16_f32 v225, v172, v173
	s_nop 0
	v_permlane32_swap_b32_e32 v224, v226
	v_mfma_f32_32x32x16_bf16 v[98:113], v[230:233], v[234:237], v[98:113]
	v_cvt_pk_bf16_f32 v230, v86, v87
	v_cvt_pk_bf16_f32 v231, v88, v89
	v_cvt_pk_bf16_f32 v232, v90, v91
	v_cvt_pk_bf16_f32 v233, v92, v93
	v_cvt_pk_bf16_f32 v234, v94, v95
	v_cvt_pk_bf16_f32 v235, v96, v97
	v_permlane32_swap_b32_e32 v225, v227
	v_permlane32_swap_b32_e32 v228, v230
	v_permlane32_swap_b32_e32 v229, v231
	v_permlane32_swap_b32_e32 v232, v234
	v_permlane32_swap_b32_e32 v233, v235
	v_lshl_add_u64 v[170:171], s[16:17], 0, v[168:169]
	v_add_co_u32_e32 v86, vcc, s77, v170
	v_lshl_add_u64 v[172:173], s[16:17], 0, v[158:159]
	s_nop 0
	v_addc_co_u32_e32 v87, vcc, 0, v171, vcc
	v_add_co_u32_e32 v90, vcc, s77, v172
	v_lshl_add_u64 v[174:175], s[16:17], 0, v[156:157]
	s_nop 0
	v_addc_co_u32_e32 v91, vcc, 0, v173, vcc
	s_mov_b32 s8, 0xb604000
	global_load_dwordx4 v[82:85], v[86:87], off offset:256
	s_nop 0
	global_load_dwordx4 v[86:89], v[86:87], off
	s_nop 0
	global_load_dwordx4 v[94:97], v[90:91], off offset:256
	s_nop 0
	global_load_dwordx4 v[90:93], v[90:91], off
	v_add_co_u32_e32 v146, vcc, s8, v174
	s_nop 1
	v_addc_co_u32_e32 v147, vcc, 0, v175, vcc
	global_load_dwordx4 v[146:149], v[146:147], off
	ds_read_b64_tr_b16 v[236:237], v180 offset:0
	ds_read_b64_tr_b16 v[238:239], v180 offset:0x800
	ds_read_b64_tr_b16 v[240:241], v180 offset:0x1000
	ds_read_b64_tr_b16 v[242:243], v180 offset:0x1800
	ds_read_b64_tr_b16 v[244:245], v180 offset:0x2000
	ds_read_b64_tr_b16 v[246:247], v180 offset:0x2800
	ds_read_b64_tr_b16 v[248:249], v180 offset:0x3000
	ds_read_b64_tr_b16 v[250:251], v180 offset:0x3800
	s_waitcnt lgkmcnt(0)
	s_nop 0
	v_mfma_f32_32x32x16_bf16 v[2:17], v[150:153], v[236:239], v[2:17]
	ds_read_b64_tr_b16 v[236:237], v180 offset:0x200
	ds_read_b64_tr_b16 v[238:239], v180 offset:0xa00
	v_mfma_f32_32x32x16_bf16 v[2:17], v[224:227], v[240:243], v[2:17]
	ds_read_b64_tr_b16 v[240:241], v180 offset:0x1200
	ds_read_b64_tr_b16 v[242:243], v180 offset:0x1a00
	v_mfma_f32_32x32x16_bf16 v[2:17], v[228:231], v[244:247], v[2:17]
	ds_read_b64_tr_b16 v[244:245], v180 offset:0x2200
	ds_read_b64_tr_b16 v[246:247], v180 offset:0x2a00
	v_mfma_f32_32x32x16_bf16 v[2:17], v[232:235], v[248:251], v[2:17]
	ds_read_b64_tr_b16 v[248:249], v180 offset:0x3200
	ds_read_b64_tr_b16 v[250:251], v180 offset:0x3a00
	s_waitcnt lgkmcnt(0)
	v_mfma_f32_32x32x16_bf16 v[50:65], v[150:153], v[236:239], v[50:65]
	ds_read_b64_tr_b16 v[236:237], v180 offset:0x400
	ds_read_b64_tr_b16 v[238:239], v180 offset:0xc00
	v_mfma_f32_32x32x16_bf16 v[50:65], v[224:227], v[240:243], v[50:65]
	ds_read_b64_tr_b16 v[240:241], v180 offset:0x1400
	ds_read_b64_tr_b16 v[242:243], v180 offset:0x1c00
	v_mfma_f32_32x32x16_bf16 v[50:65], v[228:231], v[244:247], v[50:65]
	ds_read_b64_tr_b16 v[244:245], v180 offset:0x2400
	ds_read_b64_tr_b16 v[246:247], v180 offset:0x2c00
	v_mfma_f32_32x32x16_bf16 v[50:65], v[232:235], v[248:251], v[50:65]
	ds_read_b64_tr_b16 v[248:249], v180 offset:0x3400
	ds_read_b64_tr_b16 v[250:251], v180 offset:0x3c00
	s_waitcnt lgkmcnt(0)
	v_mfma_f32_32x32x16_bf16 v[34:49], v[150:153], v[236:239], v[34:49]
	ds_read_b64_tr_b16 v[236:237], v180 offset:0x600
	ds_read_b64_tr_b16 v[238:239], v180 offset:0xe00
	v_mfma_f32_32x32x16_bf16 v[34:49], v[224:227], v[240:243], v[34:49]
	ds_read_b64_tr_b16 v[240:241], v180 offset:0x1600
	ds_read_b64_tr_b16 v[242:243], v180 offset:0x1e00
	v_mfma_f32_32x32x16_bf16 v[34:49], v[228:231], v[244:247], v[34:49]
	ds_read_b64_tr_b16 v[244:245], v180 offset:0x2600
	ds_read_b64_tr_b16 v[246:247], v180 offset:0x2e00
	v_mfma_f32_32x32x16_bf16 v[34:49], v[232:235], v[248:251], v[34:49]
	ds_read_b64_tr_b16 v[248:249], v180 offset:0x3600
	ds_read_b64_tr_b16 v[250:251], v180 offset:0x3e00
	s_waitcnt lgkmcnt(0)
	v_mfma_f32_32x32x16_bf16 v[18:33], v[150:153], v[236:239], v[18:33]
	v_max_f32_e32 v150, v115, v115
	v_max_f32_e32 v151, v114, v114
	v_max_f32_e32 v150, v151, v150
	v_max3_f32 v150, v150, v116, v117
	v_max3_f32 v150, v150, v118, v119
	v_max3_f32 v150, v150, v120, v121
	v_max3_f32 v150, v150, v122, v123
	v_mfma_f32_32x32x16_bf16 v[18:33], v[224:227], v[240:243], v[18:33]
	v_max3_f32 v150, v150, v124, v125
	v_max3_f32 v150, v150, v126, v127
	v_max3_f32 v150, v150, v128, v129
	v_max3_f32 v150, v150, v98, v99
	v_max3_f32 v150, v150, v100, v101
	v_max3_f32 v150, v150, v102, v103
	v_max3_f32 v150, v150, v104, v105
	v_mfma_f32_32x32x16_bf16 v[18:33], v[228:231], v[244:247], v[18:33]
	v_max3_f32 v150, v150, v106, v107
	v_max3_f32 v150, v150, v108, v109
	v_max3_f32 v150, v150, v110, v111
	v_max3_f32 v150, v150, v112, v113
	v_mov_b32_e32 v151, v150
	s_nop 1
	v_permlane32_swap_b32_e32 v150, v151
	v_mfma_f32_32x32x16_bf16 v[18:33], v[232:235], v[248:251], v[18:33]
	s_waitcnt vmcnt(0)
	ds_write_b128 v182, v[86:89] offset:32768
	ds_write_b128 v183, v[90:93] offset:32768
	v_add_u32_e32 v252, 0x10000, v214
	ds_write_b128 v252, v[146:149]
	v_max_f32_e32 v151, v151, v151
	v_max_f32_e32 v150, v150, v150
	v_max_f32_e32 v150, v150, v151
	v_cmp_ge_f32_e32 vcc, s12, v150
	s_cmp_eq_u64 vcc, exec
	s_cbranch_scc0 .LBB0_736
	v_mov_b32_e32 v223, 1.0
; #define SBAR() __builtin_amdgcn_sched_barrier(0)
; #define SWRITE(b) do { *(bf16x8*)(V_lds + (b) * SHM_V + vst0) = vs0; *(bf16x8*)(V_lds + (b) * SHM_V + vst1) = vs1; \
;     if constexpr (MLA) { *(bf16x8*)(KN_lds + (b) * SHM_KN + KSWZ(sr, sc * 2)) = kn0; *(bf16x8*)(KN_lds + (b) * SHM_KN + KSWZ(32 + sr, sc * 2)) = kn1; } \
;     *(bf16x8*)(KR_lds + (b) * SHM_KR + KSWZ2(kr_r, kr_c * 2)) = kr0; } while (0)
; #define SWAIT() asm volatile("s_waitcnt vmcnt(0)" ::: "memory")
; #define RESC(a) do { if (__any((a) < 1.f)) { if (hi == 0) al_l[r32] = (a); asm volatile("s_waitcnt lgkmcnt(0)" ::: "memory"); \
;     _Pragma("unroll") for (int d = 0; d < 4; ++d) _Pragma("unroll") for (int r = 0; r < 16; ++r) o[d][r] *= al_l[crow(r, hi)]; } } while (0)
; __device__ __forceinline__ void finishSM(f32x16& p0, f32x16& p1, float alpha, float& l_reg, bf16x8& pa0, bf16x8& pa1, bf16x8& pa2, bf16x8& pa3) {
; #pragma unroll
;   for (int r = 0; r < 16; ++r) p1[r] = __builtin_amdgcn_exp2f(p1[r]);
;   float ps = 0;
; #pragma unroll
;   for (int r = 0; r < 16; ++r) ps += p0[r];
; #pragma unroll
;   for (int r = 0; r < 16; ++r) ps += p1[r];
;   { auto rr = __builtin_amdgcn_permlane32_swap(__float_as_uint(ps), __float_as_uint(ps), false, false);
;     ps = __uint_as_float(rr[0]) + __uint_as_float(rr[1]); }
;   l_reg = l_reg * alpha + ps;
; template <bool MLA> ...
;     ...
;     __syncthreads(); SWAIT(); SWRITE(0);
;     RESC(alB); __syncthreads();
;     SBAR(); qkt_mla(pA0, pA1, KN_lds, KR_lds, QR_w, qr, negm, r32, hi);
.LBB0_725:
	s_barrier
	s_waitcnt vmcnt(0)
	s_waitcnt vmcnt(4)
	ds_write_b128 v184, v[82:85]
	s_waitcnt vmcnt(2)
	ds_write_b128 v185, v[94:97]
	v_cmp_gt_f32_e32 vcc, 1.0, v223
	s_cbranch_vccz .LBB0_729
	s_and_saveexec_b64 s[8:9], s[38:39]
	ds_write_b32 v176, v223 offset:128
	s_or_b64 exec, exec, s[8:9]
	s_waitcnt lgkmcnt(0)
	v_add_u32_e32 v94, s10, v160
	ds_read_b128 v[82:85], v94 offset:224
	ds_read_b128 v[86:89], v94 offset:192
	ds_read_b128 v[90:93], v94 offset:160
	ds_read_b128 v[94:97], v94 offset:128
	s_waitcnt lgkmcnt(3)
	v_pk_mul_f32 v[14:15], v[14:15], v[82:83]
	s_waitcnt lgkmcnt(2)
	v_pk_mul_f32 v[10:11], v[10:11], v[86:87]
	s_waitcnt lgkmcnt(1)
	v_pk_mul_f32 v[6:7], v[6:7], v[90:91]
	v_pk_mul_f32 v[16:17], v[16:17], v[84:85]
	v_pk_mul_f32 v[12:13], v[12:13], v[88:89]
	v_pk_mul_f32 v[8:9], v[8:9], v[92:93]
	s_waitcnt lgkmcnt(0)
	v_pk_mul_f32 v[4:5], v[4:5], v[96:97]
	v_pk_mul_f32 v[2:3], v[2:3], v[94:95]
	v_pk_mul_f32 v[62:63], v[62:63], v[82:83]
	v_pk_mul_f32 v[58:59], v[58:59], v[86:87]
	v_pk_mul_f32 v[54:55], v[54:55], v[90:91]
	v_pk_mul_f32 v[64:65], v[64:65], v[84:85]
	v_pk_mul_f32 v[60:61], v[60:61], v[88:89]
	v_pk_mul_f32 v[56:57], v[56:57], v[92:93]
	v_pk_mul_f32 v[52:53], v[52:53], v[96:97]
	v_pk_mul_f32 v[50:51], v[50:51], v[94:95]
	v_pk_mul_f32 v[46:47], v[46:47], v[82:83]
	v_pk_mul_f32 v[42:43], v[42:43], v[86:87]
	v_pk_mul_f32 v[38:39], v[38:39], v[90:91]
	v_pk_mul_f32 v[48:49], v[48:49], v[84:85]
	v_pk_mul_f32 v[44:45], v[44:45], v[88:89]
	v_pk_mul_f32 v[40:41], v[40:41], v[92:93]
	v_pk_mul_f32 v[36:37], v[36:37], v[96:97]
	v_pk_mul_f32 v[34:35], v[34:35], v[94:95]
	v_pk_mul_f32 v[30:31], v[30:31], v[82:83]
	v_pk_mul_f32 v[26:27], v[26:27], v[86:87]
	v_pk_mul_f32 v[22:23], v[22:23], v[90:91]
	v_pk_mul_f32 v[32:33], v[32:33], v[84:85]
	v_pk_mul_f32 v[28:29], v[28:29], v[88:89]
	v_pk_mul_f32 v[24:25], v[24:25], v[92:93]
	v_pk_mul_f32 v[20:21], v[20:21], v[96:97]
	v_pk_mul_f32 v[18:19], v[18:19], v[94:95]
.LBB0_729:
	v_exp_f32_e32 v150, v114
	v_exp_f32_e32 v151, v115
	v_exp_f32_e32 v149, v122
	v_exp_f32_e32 v146, v126
	v_exp_f32_e32 v147, v127
	v_exp_f32_e32 v148, v128
	v_exp_f32_e32 v152, v116
	v_exp_f32_e32 v231, v117
	v_exp_f32_e32 v232, v118
	v_exp_f32_e32 v233, v119
	v_exp_f32_e32 v153, v120
	v_exp_f32_e32 v230, v121
	v_exp_f32_e32 v227, v123
	v_exp_f32_e32 v228, v124
	v_exp_f32_e32 v229, v125
	v_exp_f32_e32 v226, v129
	s_waitcnt lgkmcnt(0)
	s_barrier
	ds_read_b128 v[82:85], v181 offset:32768
	ds_read_b128 v[234:237], v181 offset:40960
	v_add_f32_e32 v166, 0, v150
	v_add_f32_e32 v166, v151, v166
	v_add_f32_e32 v166, v152, v166
	s_waitcnt lgkmcnt(1)
	v_mfma_f32_32x32x16_bf16 v[114:129], v[82:85], v[142:145], v[66:81]
	v_add_f32_e32 v166, v231, v166
	v_add_f32_e32 v166, v232, v166
	v_add_f32_e32 v166, v233, v166
	v_add_f32_e32 v166, v153, v166
	v_add_f32_e32 v166, v230, v166
	v_add_f32_e32 v166, v149, v166
	v_add_f32_e32 v166, v227, v166
	s_waitcnt lgkmcnt(0)
	v_mfma_f32_32x32x16_bf16 v[82:97], v[234:237], v[142:145], v[66:81]
	ds_read_b128 v[234:237], v192 offset:32768
	ds_read_b128 v[238:241], v192 offset:40960
	v_add_f32_e32 v166, v228, v166
	v_add_f32_e32 v166, v229, v166
	v_exp_f32_e32 v98, v98
	v_add_f32_e32 v166, v146, v166
	v_exp_f32_e32 v99, v99
	v_add_f32_e32 v166, v147, v166
	s_waitcnt lgkmcnt(1)
	v_mfma_f32_32x32x16_bf16 v[114:129], v[234:237], v[138:141], v[114:129]
	v_exp_f32_e32 v100, v100
	v_add_f32_e32 v166, v148, v166
	v_exp_f32_e32 v101, v101
	v_add_f32_e32 v166, v226, v166
	v_exp_f32_e32 v102, v102
	v_add_f32_e32 v166, v98, v166
	v_exp_f32_e32 v103, v103
	s_waitcnt lgkmcnt(0)
	v_mfma_f32_32x32x16_bf16 v[82:97], v[238:241], v[138:141], v[82:97]
	ds_read_b128 v[234:237], v193 offset:32768
	ds_read_b128 v[238:241], v193 offset:40960
	v_add_f32_e32 v166, v99, v166
	v_exp_f32_e32 v104, v104
	v_add_f32_e32 v166, v100, v166
	v_exp_f32_e32 v105, v105
	v_add_f32_e32 v166, v101, v166
	v_exp_f32_e32 v106, v106
	s_waitcnt lgkmcnt(1)
	v_mfma_f32_32x32x16_bf16 v[114:129], v[234:237], v[134:137], v[114:129]
	v_add_f32_e32 v166, v102, v166
	v_exp_f32_e32 v107, v107
	v_add_f32_e32 v166, v103, v166
	v_exp_f32_e32 v108, v108
	v_add_f32_e32 v166, v104, v166
	v_exp_f32_e32 v109, v109
	v_add_f32_e32 v166, v105, v166
	s_waitcnt lgkmcnt(0)
	v_mfma_f32_32x32x16_bf16 v[82:97], v[238:241], v[134:137], v[82:97]
	ds_read_b128 v[234:237], v195 offset:32768
	ds_read_b128 v[238:241], v195 offset:40960
	v_exp_f32_e32 v110, v110
	v_add_f32_e32 v166, v106, v166
	v_exp_f32_e32 v111, v111
	v_add_f32_e32 v166, v107, v166
	v_exp_f32_e32 v112, v112
	v_add_f32_e32 v166, v108, v166
	s_waitcnt lgkmcnt(1)
	v_mfma_f32_32x32x16_bf16 v[114:129], v[234:237], v[130:133], v[114:129]
	v_exp_f32_e32 v113, v113
	v_add_f32_e32 v166, v109, v166
	v_add_f32_e32 v166, v110, v166
	v_add_f32_e32 v166, v111, v166
	v_add_f32_e32 v166, v112, v166
	v_add_f32_e32 v224, v113, v166
	v_mov_b32_e32 v225, v224
	s_waitcnt lgkmcnt(0)
	v_mfma_f32_32x32x16_bf16 v[82:97], v[238:241], v[130:133], v[82:97]
	ds_read_b128 v[234:237], v197 offset:32768
	ds_read_b128 v[238:241], v197 offset:40960
	ds_read_b128 v[242:245], v199
	v_cvt_pk_bf16_f32 v150, v150, v151
	v_cvt_pk_bf16_f32 v151, v152, v231
	v_cvt_pk_bf16_f32 v152, v232, v233
	v_cvt_pk_bf16_f32 v153, v153, v230
	v_permlane32_swap_b32_e32 v224, v225
	s_waitcnt lgkmcnt(0)
	v_mfma_f32_32x32x16_bf16 v[114:129], v[234:237], v[242:245], v[114:129]
	v_permlane32_swap_b32_e32 v150, v152
	v_permlane32_swap_b32_e32 v151, v153
	v_cvt_pk_bf16_f32 v230, v149, v227
	v_cvt_pk_bf16_f32 v231, v228, v229
	v_cvt_pk_bf16_f32 v232, v146, v147
	v_mfma_f32_32x32x16_bf16 v[82:97], v[238:241], v[242:245], v[82:97]
	ds_read_b128 v[234:237], v191 offset:32768
	ds_read_b128 v[238:241], v191 offset:40960
	ds_read_b128 v[242:245], v201
	v_cvt_pk_bf16_f32 v233, v148, v226
	v_cvt_pk_bf16_f32 v226, v98, v99
	v_cvt_pk_bf16_f32 v227, v100, v101
	v_cvt_pk_bf16_f32 v228, v102, v103
	v_cvt_pk_bf16_f32 v229, v104, v105
	v_permlane32_swap_b32_e32 v230, v232
	s_waitcnt lgkmcnt(0)
; #define SBAR() __builtin_amdgcn_sched_barrier(0)
; #define PVF(...) do { if constexpr (!MLA || ATT_PIPE_MLA) pv_pipe(__VA_ARGS__); else pv_d0(__VA_ARGS__); } while (0)
; template <int D0> __device__ __forceinline__ void pv_one(f32x16& od, int vb, bf16x8 pa0, bf16x8 pa1, bf16x8 pa2, bf16x8 pa3) {
;   const s16x4 l0 = tr_read<v_rd_off(D0, 0, 0)>(vb), h0 = tr_read<v_rd_off(D0, 0, 1)>(vb), l1 = tr_read<v_rd_off(D0, 1, 0)>(vb), h1 = tr_read<v_rd_off(D0, 1, 1)>(vb);
;   const s16x4 l2 = tr_read<v_rd_off(D0, 2, 0)>(vb), h2 = tr_read<v_rd_off(D0, 2, 1)>(vb), l3 = tr_read<v_rd_off(D0, 3, 0)>(vb), h3 = tr_read<v_rd_off(D0, 3, 1)>(vb);
;   asm volatile("s_waitcnt lgkmcnt(0)" ::: "memory"); SBAR();
;     ...
;   od = __builtin_amdgcn_mfma_f32_32x32x16_bf16(pa0, PK(l0, h0), od, 0, 0, 0);
;   od = __builtin_amdgcn_mfma_f32_32x32x16_bf16(pa1, PK(l1, h1), od, 0, 0, 0);
;   od = __builtin_amdgcn_mfma_f32_32x32x16_bf16(pa2, PK(l2, h2), od, 0, 0, 0);
;   od = __builtin_amdgcn_mfma_f32_32x32x16_bf16(pa3, PK(l3, h3), od, 0, 0, 0);
;     ...
; }
; __device__ __forceinline__ void pv_d0(f32x16* o, int vb, bf16x8 pa0, bf16x8 pa1, bf16x8 pa2, bf16x8 pa3) {
;   pv_one<0>(o[0], vb, pa0, pa1, pa2, pa3); pv_one<1>(o[1], vb, pa0, pa1, pa2, pa3); pv_one<2>(o[2], vb, pa0, pa1, pa2, pa3); pv_one<3>(o[3], vb, pa0, pa1, pa2, pa3);
; template <bool MLA> ...
;     ...
;     SBAR(); qkt_mla(pA0, pA1, KN_lds, KR_lds, QR_w, qr, negm, r32, hi);
;     finishSM(pB0, pB1, alB, l_reg, pa0, pa1, pa2, pa3); SBAR();
;     SLOAD((j + 2) * KVBLK); SBAR();
;     PVF(o, vb0 + SHM_V, pa0, pa1, pa2, pa3); partialSM_pre<false>(pA0, pA1, Mref, negm, alA);
	v_mfma_f32_32x32x16_bf16 v[114:129], v[234:237], v[242:245], v[114:129]
	v_permlane32_swap_b32_e32 v231, v233
	v_permlane32_swap_b32_e32 v226, v228
	v_permlane32_swap_b32_e32 v227, v229
	v_mfma_f32_32x32x16_bf16 v[82:97], v[238:241], v[242:245], v[82:97]
	ds_read_b128 v[234:237], v196 offset:32768
	ds_read_b128 v[238:241], v196 offset:40960
	ds_read_b128 v[242:245], v200
	s_waitcnt lgkmcnt(0)
	v_mfma_f32_32x32x16_bf16 v[114:129], v[234:237], v[242:245], v[114:129]
	v_mfma_f32_32x32x16_bf16 v[82:97], v[238:241], v[242:245], v[82:97]
	ds_read_b128 v[234:237], v194 offset:32768
	ds_read_b128 v[238:241], v194 offset:40960
	ds_read_b128 v[242:245], v204
	s_waitcnt lgkmcnt(0)
	v_mfma_f32_32x32x16_bf16 v[114:129], v[234:237], v[242:245], v[114:129]
	v_mfma_f32_32x32x16_bf16 v[82:97], v[238:241], v[242:245], v[82:97]
	ds_read_b128 v[234:237], v207
	ds_read_b128 v[238:241], v207 offset:4096
	ds_read_b128 v[242:245], v205
	s_waitcnt lgkmcnt(0)
	v_mfma_f32_32x32x16_bf16 v[114:129], v[234:237], v[242:245], v[114:129]
	v_mfma_f32_32x32x16_bf16 v[82:97], v[238:241], v[242:245], v[82:97]
	ds_read_b128 v[234:237], v209
	ds_read_b128 v[238:241], v209 offset:4096
	ds_read_b128 v[242:245], v203
	s_waitcnt lgkmcnt(0)
	v_mfma_f32_32x32x16_bf16 v[114:129], v[234:237], v[242:245], v[114:129]
	v_mfma_f32_32x32x16_bf16 v[82:97], v[238:241], v[242:245], v[82:97]
	ds_read_b128 v[234:237], v211
	ds_read_b128 v[238:241], v211 offset:4096
	ds_read_b128 v[242:245], v202
	s_waitcnt lgkmcnt(0)
	v_mfma_f32_32x32x16_bf16 v[114:129], v[234:237], v[242:245], v[114:129]
	v_mfma_f32_32x32x16_bf16 v[82:97], v[238:241], v[242:245], v[82:97]
	ds_read_b128 v[234:237], v213
	ds_read_b128 v[238:241], v213 offset:4096
	ds_read_b128 v[242:245], v198
	s_waitcnt lgkmcnt(0)
	v_mfma_f32_32x32x16_bf16 v[114:129], v[234:237], v[242:245], v[114:129]
	v_cvt_pk_bf16_f32 v234, v106, v107
	v_cvt_pk_bf16_f32 v235, v108, v109
	v_cvt_pk_bf16_f32 v236, v110, v111
	v_cvt_pk_bf16_f32 v237, v112, v113
	s_nop 0
	v_permlane32_swap_b32_e32 v234, v236
	v_permlane32_swap_b32_e32 v235, v237
	v_mfma_f32_32x32x16_bf16 v[82:97], v[238:241], v[242:245], v[82:97]
	v_add_co_u32_e32 v102, vcc, s64, v170
	s_mov_b32 s8, 0xb606000
	s_nop 0
	v_addc_co_u32_e32 v103, vcc, 0, v171, vcc
	v_add_co_u32_e32 v106, vcc, s64, v172
	s_nop 1
	v_addc_co_u32_e32 v107, vcc, 0, v173, vcc
	global_load_dwordx4 v[98:101], v[102:103], off offset:256
	s_nop 0
	global_load_dwordx4 v[102:105], v[102:103], off
	s_nop 0
	global_load_dwordx4 v[110:113], v[106:107], off offset:256
	s_nop 0
	global_load_dwordx4 v[106:109], v[106:107], off
	v_add_co_u32_e32 v146, vcc, s8, v174
	s_nop 1
	v_addc_co_u32_e32 v147, vcc, 0, v175, vcc
	global_load_dwordx4 v[146:149], v[146:147], off
	ds_read_b64_tr_b16 v[170:171], v178 offset:0
	ds_read_b64_tr_b16 v[172:173], v178 offset:0x800
	ds_read_b64_tr_b16 v[238:239], v178 offset:0x1000
	ds_read_b64_tr_b16 v[240:241], v178 offset:0x1800
	ds_read_b64_tr_b16 v[242:243], v178 offset:0x2000
	ds_read_b64_tr_b16 v[244:245], v178 offset:0x2800
	ds_read_b64_tr_b16 v[246:247], v178 offset:0x3000
	ds_read_b64_tr_b16 v[248:249], v178 offset:0x3800
	s_waitcnt lgkmcnt(0)
	s_nop 0
	v_mfma_f32_32x32x16_bf16 v[2:17], v[150:153], v[170:173], v[2:17]
	ds_read_b64_tr_b16 v[170:171], v178 offset:0x200
	ds_read_b64_tr_b16 v[172:173], v178 offset:0xa00
	v_mfma_f32_32x32x16_bf16 v[2:17], v[230:233], v[238:241], v[2:17]
	ds_read_b64_tr_b16 v[238:239], v178 offset:0x1200
	ds_read_b64_tr_b16 v[240:241], v178 offset:0x1a00
	v_mfma_f32_32x32x16_bf16 v[2:17], v[226:229], v[242:245], v[2:17]
	ds_read_b64_tr_b16 v[242:243], v178 offset:0x2200
	ds_read_b64_tr_b16 v[244:245], v178 offset:0x2a00
	v_mfma_f32_32x32x16_bf16 v[2:17], v[234:237], v[246:249], v[2:17]
	ds_read_b64_tr_b16 v[246:247], v178 offset:0x3200
	ds_read_b64_tr_b16 v[248:249], v178 offset:0x3a00
	s_waitcnt lgkmcnt(0)
	v_mfma_f32_32x32x16_bf16 v[50:65], v[150:153], v[170:173], v[50:65]
	ds_read_b64_tr_b16 v[170:171], v178 offset:0x400
	ds_read_b64_tr_b16 v[172:173], v178 offset:0xc00
	v_mfma_f32_32x32x16_bf16 v[50:65], v[230:233], v[238:241], v[50:65]
	ds_read_b64_tr_b16 v[238:239], v178 offset:0x1400
	ds_read_b64_tr_b16 v[240:241], v178 offset:0x1c00
	v_mfma_f32_32x32x16_bf16 v[50:65], v[226:229], v[242:245], v[50:65]
	ds_read_b64_tr_b16 v[242:243], v178 offset:0x2400
	ds_read_b64_tr_b16 v[244:245], v178 offset:0x2c00
	v_mfma_f32_32x32x16_bf16 v[50:65], v[234:237], v[246:249], v[50:65]
	ds_read_b64_tr_b16 v[246:247], v178 offset:0x3400
	ds_read_b64_tr_b16 v[248:249], v178 offset:0x3c00
	s_waitcnt lgkmcnt(0)
	v_mfma_f32_32x32x16_bf16 v[34:49], v[150:153], v[170:173], v[34:49]
	ds_read_b64_tr_b16 v[170:171], v178 offset:0x600
	ds_read_b64_tr_b16 v[172:173], v178 offset:0xe00
	v_mfma_f32_32x32x16_bf16 v[34:49], v[230:233], v[238:241], v[34:49]
	ds_read_b64_tr_b16 v[238:239], v178 offset:0x1600
	ds_read_b64_tr_b16 v[240:241], v178 offset:0x1e00
	v_mfma_f32_32x32x16_bf16 v[34:49], v[226:229], v[242:245], v[34:49]
	ds_read_b64_tr_b16 v[242:243], v178 offset:0x2600
	ds_read_b64_tr_b16 v[244:245], v178 offset:0x2e00
	v_mfma_f32_32x32x16_bf16 v[34:49], v[234:237], v[246:249], v[34:49]
	ds_read_b64_tr_b16 v[246:247], v178 offset:0x3600
	ds_read_b64_tr_b16 v[248:249], v178 offset:0x3e00
	s_waitcnt lgkmcnt(0)
	v_mfma_f32_32x32x16_bf16 v[18:33], v[150:153], v[170:173], v[18:33]
	v_max_f32_e32 v150, v115, v115
	v_max_f32_e32 v151, v114, v114
	v_max_f32_e32 v150, v151, v150
	v_max3_f32 v150, v150, v116, v117
	v_max3_f32 v150, v150, v118, v119
	v_max3_f32 v150, v150, v120, v121
	v_max3_f32 v150, v150, v122, v123
	v_mfma_f32_32x32x16_bf16 v[18:33], v[230:233], v[238:241], v[18:33]
	v_max3_f32 v150, v150, v124, v125
	v_max3_f32 v150, v150, v126, v127
	v_max3_f32 v150, v150, v128, v129
	v_max3_f32 v150, v150, v82, v83
	v_max3_f32 v150, v150, v84, v85
	v_max3_f32 v150, v150, v86, v87
	v_max3_f32 v150, v150, v88, v89
	v_mfma_f32_32x32x16_bf16 v[18:33], v[226:229], v[242:245], v[18:33]
	v_max3_f32 v150, v150, v90, v91
	v_max3_f32 v150, v150, v92, v93
	v_max3_f32 v150, v150, v94, v95
	v_max3_f32 v150, v150, v96, v97
	v_mov_b32_e32 v151, v150
	s_nop 1
	v_permlane32_swap_b32_e32 v150, v151
	v_mfma_f32_32x32x16_bf16 v[18:33], v[234:237], v[246:249], v[18:33]
	s_waitcnt vmcnt(0)
	ds_write_b128 v182, v[102:105] offset:49152
	ds_write_b128 v183, v[106:109] offset:49152
	ds_write_b128 v215, v[146:149]
	v_max_f32_e32 v151, v151, v151
	v_max_f32_e32 v150, v150, v150
	v_max_f32_e32 v151, v150, v151
	v_cmp_ge_f32_e32 vcc, s12, v151
	s_cmp_eq_u64 vcc, exec
	v_mov_b32_e32 v150, 1.0
	s_cbranch_scc0 .LBB0_737
; #define SWRITE(b) do { *(bf16x8*)(V_lds + (b) * SHM_V + vst0) = vs0; *(bf16x8*)(V_lds + (b) * SHM_V + vst1) = vs1; \
;     if constexpr (MLA) { *(bf16x8*)(KN_lds + (b) * SHM_KN + KSWZ(sr, sc * 2)) = kn0; *(bf16x8*)(KN_lds + (b) * SHM_KN + KSWZ(32 + sr, sc * 2)) = kn1; } \
;     *(bf16x8*)(KR_lds + (b) * SHM_KR + KSWZ2(kr_r, kr_c * 2)) = kr0; } while (0)
; #define SWAIT() asm volatile("s_waitcnt vmcnt(0)" ::: "memory")
; #define RESC(a) do { if (__any((a) < 1.f)) { if (hi == 0) al_l[r32] = (a); asm volatile("s_waitcnt lgkmcnt(0)" ::: "memory"); \
;     _Pragma("unroll") for (int d = 0; d < 4; ++d) _Pragma("unroll") for (int r = 0; r < 16; ++r) o[d][r] *= al_l[crow(r, hi)]; } } while (0)
; template <bool MLA> ...
;     ...
;     __syncthreads(); SWAIT(); SWRITE(1);
;     RESC(alA); __syncthreads();
.LBB0_730:
	s_barrier
	s_waitcnt vmcnt(0)
	v_cmp_gt_f32_e32 vcc, 1.0, v150
	s_waitcnt vmcnt(4)
	ds_write_b128 v184, v[98:101] offset:16384
	s_waitcnt vmcnt(2)
	ds_write_b128 v185, v[110:113] offset:16384
	s_cbranch_vccz .LBB0_734
	s_and_saveexec_b64 s[8:9], s[38:39]
	ds_write_b32 v176, v150 offset:128
	s_or_b64 exec, exec, s[8:9]
	s_waitcnt lgkmcnt(0)
	v_add_u32_e32 v110, s10, v160
	ds_read_b128 v[98:101], v110 offset:224
	ds_read_b128 v[102:105], v110 offset:192
	ds_read_b128 v[106:109], v110 offset:160
	ds_read_b128 v[110:113], v110 offset:128
	s_waitcnt lgkmcnt(3)
	v_pk_mul_f32 v[14:15], v[14:15], v[98:99]
	s_waitcnt lgkmcnt(2)
	v_pk_mul_f32 v[10:11], v[10:11], v[102:103]
	s_waitcnt lgkmcnt(1)
	v_pk_mul_f32 v[6:7], v[6:7], v[106:107]
	v_pk_mul_f32 v[16:17], v[16:17], v[100:101]
	v_pk_mul_f32 v[12:13], v[12:13], v[104:105]
	v_pk_mul_f32 v[8:9], v[8:9], v[108:109]
	s_waitcnt lgkmcnt(0)
	v_pk_mul_f32 v[4:5], v[4:5], v[112:113]
	v_pk_mul_f32 v[2:3], v[2:3], v[110:111]
	v_pk_mul_f32 v[62:63], v[62:63], v[98:99]
	v_pk_mul_f32 v[58:59], v[58:59], v[102:103]
	v_pk_mul_f32 v[54:55], v[54:55], v[106:107]
	v_pk_mul_f32 v[64:65], v[64:65], v[100:101]
	v_pk_mul_f32 v[60:61], v[60:61], v[104:105]
	v_pk_mul_f32 v[56:57], v[56:57], v[108:109]
	v_pk_mul_f32 v[52:53], v[52:53], v[112:113]
	v_pk_mul_f32 v[50:51], v[50:51], v[110:111]
	v_pk_mul_f32 v[46:47], v[46:47], v[98:99]
	v_pk_mul_f32 v[42:43], v[42:43], v[102:103]
	v_pk_mul_f32 v[38:39], v[38:39], v[106:107]
	v_pk_mul_f32 v[48:49], v[48:49], v[100:101]
	v_pk_mul_f32 v[44:45], v[44:45], v[104:105]
	v_pk_mul_f32 v[40:41], v[40:41], v[108:109]
	v_pk_mul_f32 v[36:37], v[36:37], v[112:113]
	v_pk_mul_f32 v[34:35], v[34:35], v[110:111]
	v_pk_mul_f32 v[30:31], v[30:31], v[98:99]
	v_pk_mul_f32 v[26:27], v[26:27], v[102:103]
	v_pk_mul_f32 v[22:23], v[22:23], v[106:107]
	v_pk_mul_f32 v[32:33], v[32:33], v[100:101]
	v_pk_mul_f32 v[28:29], v[28:29], v[104:105]
	v_pk_mul_f32 v[24:25], v[24:25], v[108:109]
	v_pk_mul_f32 v[20:21], v[20:21], v[112:113]
	v_pk_mul_f32 v[18:19], v[18:19], v[110:111]
